# slot fusion v7: pass-1 row copy overlapped with phase 6, fp8 table conversion (both layers) overlapped with phase 9 of pass 0
# speedup vs baseline: 1.0003x; 1.0003x over previous
; DEVI float sigmoidf_(float x) { return 1.f / (1.f + __expf(-x)); }
; template <int BR, int IN, int OUT>
; DEVI void p6_branch(const Params& P, int pm, int pn, float* macc, char* smem, int tid) {
;     ...
; #pragma unroll 8
;   for (int q = 0; q < 16; ++q) {
;     const int id = tid + 256 * q, row = id >> 5, c4 = id & 31;
;     const long grow = (long)pm * 128 + row;
;     const int gcol = pn * 128 + c4 * 4;
;     float4 a = *reinterpret_cast<const float4*>(T + row * 128 + c4 * 4);
;     float g[4];
;     load4bf(Z + grow * NCOL + (9 + BR) * 1024 + gcol, g);
;     float v[4] = {sigmoidf_(g[0]) * a.x, sigmoidf_(g[1]) * a.y, sigmoidf_(g[2]) * a.z, sigmoidf_(g[3]) * a.w};
;     if (IN == 1) {
;       float mo[4]; load4bf(M + grow * 1024 + gcol, mo);
;       v[0] += mo[0]; v[1] += mo[1]; v[2] += mo[2]; v[3] += mo[3];
;     }
;     if (IN == 2) {
;       float4 mo = *reinterpret_cast<const float4*>(macc + grow * 1024 + gcol);
;       v[0] += mo.x; v[1] += mo.y; v[2] += mo.z; v[3] += mo.w;
;     }
;     if (OUT == 1) *reinterpret_cast<float4*>(macc + grow * 1024 + gcol) = make_float4(v[0], v[1], v[2], v[3]);
;     else store4bf(M + grow * 1024 + gcol, v);
;   }
.LBB0_741:
	v_add_u32_e32 v238, s24, v91
	v_ashrrev_i32_e32 v236, 5, v238
	v_ashrrev_i32_e32 v237, 31, v236
	v_lshl_add_u64 v[240:241], s[40:41], 0, v[236:237]
	v_mov_b64_e32 v[236:237], s[44:45]
	v_mad_u64_u32 v[242:243], s[26:27], v240, s22, v[236:237]
	v_mad_i32_i24 v243, v241, s22, v243
	v_lshl_add_u64 v[242:243], v[242:243], 0, v[4:5]
	v_add_co_u32_e32 v242, vcc, 0x5000, v242
	s_nop 1
	v_addc_co_u32_e32 v243, vcc, 0, v243, vcc
	global_load_dwordx2 v[154:155], v[242:243], off
	v_add_u32_e32 v238, s24, v91
	v_ashrrev_i32_e32 v236, 5, v238
	v_ashrrev_i32_e32 v237, 31, v236
	v_lshl_add_u64 v[240:241], s[40:41], 0, v[236:237]
	v_lshlrev_b64 v[242:243], 12, v[240:241]
	v_lshl_add_u64 v[244:245], v[0:1], 0, v[242:243]
	global_load_dwordx4 v[156:159], v[244:245], off
	v_add_u32_e32 v238, s24, v91
	v_mov_b64_e32 v[236:237], s[44:45]
	v_add_u32_e32 v239, 0x100, v238
	v_ashrrev_i32_e32 v240, 5, v239
	v_ashrrev_i32_e32 v241, 31, v240
	v_lshl_add_u64 v[242:243], s[40:41], 0, v[240:241]
	v_mad_u64_u32 v[240:241], s[26:27], v242, s22, v[236:237]
	v_mad_i32_i24 v241, v243, s22, v241
	v_lshl_add_u64 v[240:241], v[240:241], 0, v[4:5]
	v_add_co_u32_e32 v240, vcc, s21, v240
	s_nop 1
	v_addc_co_u32_e32 v241, vcc, 0, v241, vcc
	global_load_dwordx2 v[160:161], v[240:241], off
	v_add_u32_e32 v236, s24, v91
	v_add_u32_e32 v237, 0x100, v236
	v_ashrrev_i32_e32 v238, 5, v237
	v_ashrrev_i32_e32 v239, 31, v238
	v_lshl_add_u64 v[240:241], s[40:41], 0, v[238:239]
	v_lshlrev_b64 v[238:239], 12, v[240:241]
	v_lshl_add_u64 v[242:243], v[0:1], 0, v[238:239]
	global_load_dwordx4 v[164:167], v[242:243], off
	v_add_u32_e32 v238, s24, v91
	v_mov_b64_e32 v[236:237], s[44:45]
	v_add_u32_e32 v239, 0x200, v238
	v_ashrrev_i32_e32 v240, 5, v239
	v_ashrrev_i32_e32 v241, 31, v240
	v_lshl_add_u64 v[242:243], s[40:41], 0, v[240:241]
	v_mad_u64_u32 v[240:241], s[26:27], v242, s22, v[236:237]
	v_mad_i32_i24 v241, v243, s22, v241
	v_lshl_add_u64 v[240:241], v[240:241], 0, v[4:5]
	v_add_co_u32_e32 v240, vcc, s21, v240
	s_nop 1
	v_addc_co_u32_e32 v241, vcc, 0, v241, vcc
	global_load_dwordx2 v[162:163], v[240:241], off
	v_add_u32_e32 v236, s24, v91
	v_add_u32_e32 v237, 0x200, v236
	v_ashrrev_i32_e32 v238, 5, v237
	v_ashrrev_i32_e32 v239, 31, v238
	v_lshl_add_u64 v[240:241], s[40:41], 0, v[238:239]
	v_lshlrev_b64 v[238:239], 12, v[240:241]
	v_lshl_add_u64 v[242:243], v[0:1], 0, v[238:239]
	global_load_dwordx4 v[168:171], v[242:243], off
	v_add_u32_e32 v238, s24, v91
	v_mov_b64_e32 v[236:237], s[44:45]
	v_add_u32_e32 v239, 0x300, v238
	v_ashrrev_i32_e32 v240, 5, v239
	v_ashrrev_i32_e32 v241, 31, v240
	v_lshl_add_u64 v[242:243], s[40:41], 0, v[240:241]
	v_mad_u64_u32 v[240:241], s[26:27], v242, s22, v[236:237]
	v_mad_i32_i24 v241, v243, s22, v241
	v_lshl_add_u64 v[240:241], v[240:241], 0, v[4:5]
	v_add_co_u32_e32 v240, vcc, s21, v240
	s_nop 1
	v_addc_co_u32_e32 v241, vcc, 0, v241, vcc
	global_load_dwordx2 v[172:173], v[240:241], off
	v_add_u32_e32 v236, s24, v91
	v_add_u32_e32 v237, 0x300, v236
	v_ashrrev_i32_e32 v238, 5, v237
	v_ashrrev_i32_e32 v239, 31, v238
	v_lshl_add_u64 v[240:241], s[40:41], 0, v[238:239]
	v_lshlrev_b64 v[238:239], 12, v[240:241]
	v_lshl_add_u64 v[242:243], v[0:1], 0, v[238:239]
	global_load_dwordx4 v[176:179], v[242:243], off
	v_add_u32_e32 v238, s24, v91
	v_mov_b64_e32 v[236:237], s[44:45]
	v_add_u32_e32 v239, 0x400, v238
	v_ashrrev_i32_e32 v240, 5, v239
	v_ashrrev_i32_e32 v241, 31, v240
	v_lshl_add_u64 v[242:243], s[40:41], 0, v[240:241]
	v_mad_u64_u32 v[240:241], s[26:27], v242, s22, v[236:237]
	v_mad_i32_i24 v241, v243, s22, v241
	v_lshl_add_u64 v[240:241], v[240:241], 0, v[4:5]
	v_add_co_u32_e32 v240, vcc, s21, v240
	s_nop 1
	v_addc_co_u32_e32 v241, vcc, 0, v241, vcc
	global_load_dwordx2 v[174:175], v[240:241], off
	v_add_u32_e32 v236, s24, v91
	v_add_u32_e32 v237, 0x400, v236
	v_ashrrev_i32_e32 v238, 5, v237
	v_ashrrev_i32_e32 v239, 31, v238
	v_lshl_add_u64 v[240:241], s[40:41], 0, v[238:239]
	v_lshlrev_b64 v[238:239], 12, v[240:241]
	v_lshl_add_u64 v[242:243], v[0:1], 0, v[238:239]
	global_load_dwordx4 v[180:183], v[242:243], off
	v_add_u32_e32 v238, s24, v91
	v_mov_b64_e32 v[236:237], s[44:45]
	v_add_u32_e32 v239, 0x500, v238
	v_ashrrev_i32_e32 v240, 5, v239
	v_ashrrev_i32_e32 v241, 31, v240
	v_lshl_add_u64 v[242:243], s[40:41], 0, v[240:241]
	v_mad_u64_u32 v[240:241], s[26:27], v242, s22, v[236:237]
	v_mad_i32_i24 v241, v243, s22, v241
	v_lshl_add_u64 v[240:241], v[240:241], 0, v[4:5]
	v_add_co_u32_e32 v240, vcc, s21, v240
	s_nop 1
	v_addc_co_u32_e32 v241, vcc, 0, v241, vcc
	global_load_dwordx2 v[208:209], v[240:241], off
	v_add_u32_e32 v236, s24, v91
	v_add_u32_e32 v237, 0x500, v236
	v_ashrrev_i32_e32 v238, 5, v237
	v_ashrrev_i32_e32 v239, 31, v238
	v_lshl_add_u64 v[240:241], s[40:41], 0, v[238:239]
	v_lshlrev_b64 v[238:239], 12, v[240:241]
	v_lshl_add_u64 v[242:243], v[0:1], 0, v[238:239]
	global_load_dwordx4 v[212:215], v[242:243], off
	v_add_u32_e32 v238, s24, v91
	v_mov_b64_e32 v[236:237], s[44:45]
	v_add_u32_e32 v239, 0x600, v238
	v_ashrrev_i32_e32 v240, 5, v239
	v_ashrrev_i32_e32 v241, 31, v240
	v_lshl_add_u64 v[242:243], s[40:41], 0, v[240:241]
	v_mad_u64_u32 v[240:241], s[26:27], v242, s22, v[236:237]
	v_mad_i32_i24 v241, v243, s22, v241
	v_lshl_add_u64 v[240:241], v[240:241], 0, v[4:5]
	v_add_co_u32_e32 v240, vcc, s21, v240
	s_nop 1
	v_addc_co_u32_e32 v241, vcc, 0, v241, vcc
	global_load_dwordx2 v[210:211], v[240:241], off
	v_add_u32_e32 v236, s24, v91
	v_add_u32_e32 v237, 0x600, v236
	v_ashrrev_i32_e32 v238, 5, v237
	v_ashrrev_i32_e32 v239, 31, v238
	v_lshl_add_u64 v[240:241], s[40:41], 0, v[238:239]
	v_lshlrev_b64 v[238:239], 12, v[240:241]
	v_lshl_add_u64 v[242:243], v[0:1], 0, v[238:239]
	global_load_dwordx4 v[216:219], v[242:243], off
	v_add_u32_e32 v238, s24, v91
	v_mov_b64_e32 v[236:237], s[44:45]
	v_add_u32_e32 v238, 0x700, v238
	v_ashrrev_i32_e32 v238, 5, v238
	v_ashrrev_i32_e32 v239, 31, v238
	v_lshl_add_u64 v[240:241], s[40:41], 0, v[238:239]
	v_mad_u64_u32 v[236:237], s[26:27], v240, s22, v[236:237]
	v_mad_i32_i24 v237, v241, s22, v237
	v_lshl_add_u64 v[236:237], v[236:237], 0, v[4:5]
	v_add_co_u32_e32 v236, vcc, s21, v236
	s_nop 1
	v_addc_co_u32_e32 v237, vcc, 0, v237, vcc
	global_load_dwordx2 v[220:221], v[236:237], off
	v_add_u32_e32 v238, s24, v91
	v_add_u32_e32 v238, 0x700, v238
	v_ashrrev_i32_e32 v238, 5, v238
	v_ashrrev_i32_e32 v239, 31, v238
	v_lshl_add_u64 v[240:241], s[40:41], 0, v[238:239]
	v_lshlrev_b64 v[236:237], 12, v[240:241]
	v_lshl_add_u64 v[242:243], v[0:1], 0, v[236:237]
	global_load_dwordx4 v[224:227], v[242:243], off
	s_waitcnt vmcnt(0)
; DEVI float sigmoidf_(float x) { return 1.f / (1.f + __expf(-x)); }
; template <int BR, int IN, int OUT>
; DEVI void p6_branch(const Params& P, int pm, int pn, float* macc, char* smem, int tid) {
;     ...
; #pragma unroll 8
;   for (int q = 0; q < 16; ++q) {
;     const int id = tid + 256 * q, row = id >> 5, c4 = id & 31;
;     const long grow = (long)pm * 128 + row;
;     const int gcol = pn * 128 + c4 * 4;
;     float4 a = *reinterpret_cast<const float4*>(T + row * 128 + c4 * 4);
;     float g[4];
;     load4bf(Z + grow * NCOL + (9 + BR) * 1024 + gcol, g);
;     float v[4] = {sigmoidf_(g[0]) * a.x, sigmoidf_(g[1]) * a.y, sigmoidf_(g[2]) * a.z, sigmoidf_(g[3]) * a.w};
;     if (IN == 1) {
;       float mo[4]; load4bf(M + grow * 1024 + gcol, mo);
;       v[0] += mo[0]; v[1] += mo[1]; v[2] += mo[2]; v[3] += mo[3];
;     }
;     if (IN == 2) {
;       float4 mo = *reinterpret_cast<const float4*>(macc + grow * 1024 + gcol);
;       v[0] += mo.x; v[1] += mo.y; v[2] += mo.z; v[3] += mo.w;
;     }
;     if (OUT == 1) *reinterpret_cast<float4*>(macc + grow * 1024 + gcol) = make_float4(v[0], v[1], v[2], v[3]);
;     else store4bf(M + grow * 1024 + gcol, v);
;   }
	v_add_u32_e32 v8, s24, v91
	v_ashrrev_i32_e32 v6, 5, v8
	v_ashrrev_i32_e32 v7, 31, v6
	v_lshl_add_u64 v[10:11], s[40:41], 0, v[6:7]
	v_lshl_or_b32 v9, v6, 9, v152
	v_mov_b64_e32 v[6:7], s[44:45]
	v_mad_u64_u32 v[12:13], s[26:27], v10, s22, v[6:7]
	v_mad_i32_i24 v13, v11, s22, v13
	v_lshl_add_u64 v[12:13], v[12:13], 0, v[4:5]
	v_add_co_u32_e32 v12, vcc, 0x5000, v12
	s_addk_i32 s24, 0x800
	s_nop 0
	v_addc_co_u32_e32 v13, vcc, 0, v13, vcc
	v_mov_b32_e32 v12, v154
	v_mov_b32_e32 v13, v155
	s_cmpk_lg_i32 s24, 0x1000
	v_lshlrev_b32_e32 v14, 16, v12
	v_and_b32_e32 v12, 0xffff0000, v12
	v_lshlrev_b32_e32 v15, 16, v13
	v_mul_f32_e32 v12, 0xbfb8aa3b, v12
	v_mul_f32_e32 v14, 0xbfb8aa3b, v14
	v_exp_f32_e32 v16, v12
	v_mul_f32_e32 v12, 0xbfb8aa3b, v15
	v_exp_f32_e32 v14, v14
	v_exp_f32_e32 v15, v12
	v_and_b32_e32 v13, 0xffff0000, v13
	v_mul_f32_e32 v12, 0xbfb8aa3b, v13
	v_exp_f32_e32 v17, v12
	v_lshlrev_b64 v[12:13], 12, v[10:11]
	v_lshlrev_b64 v[10:11], 11, v[10:11]
	v_pk_add_f32 v[14:15], v[14:15], 1.0 op_sel_hi:[1,0]
	v_lshl_add_u64 v[18:19], v[0:1], 0, v[12:13]
	v_lshl_add_u64 v[20:21], v[2:3], 0, v[10:11]
	ds_read_b128 v[10:13], v9
	v_div_scale_f32 v9, s[26:27], v15, v15, 1.0
	v_rcp_f32_e32 v22, v9
	s_nop 0
	v_fma_f32 v23, -v9, v22, 1.0
	v_fmac_f32_e32 v22, v23, v22
	v_div_scale_f32 v23, vcc, 1.0, v15, 1.0
	v_mul_f32_e32 v24, v23, v22
	v_fma_f32 v25, -v9, v24, v23
	v_fmac_f32_e32 v24, v25, v22
	v_fma_f32 v9, -v9, v24, v23
	v_div_fmas_f32 v9, v9, v22, v24
	v_div_fixup_f32 v23, v9, v15, 1.0
	v_div_scale_f32 v9, s[26:27], v14, v14, 1.0
	v_rcp_f32_e32 v15, v9
	s_nop 0
	v_fma_f32 v22, -v9, v15, 1.0
	v_fmac_f32_e32 v15, v22, v15
	v_div_scale_f32 v22, vcc, 1.0, v14, 1.0
	v_mul_f32_e32 v24, v22, v15
	v_fma_f32 v25, -v9, v24, v22
	v_fmac_f32_e32 v24, v25, v15
	v_fma_f32 v9, -v9, v24, v22
	v_div_fmas_f32 v9, v9, v15, v24
	v_div_fixup_f32 v22, v9, v14, 1.0
	v_pk_add_f32 v[14:15], v[16:17], 1.0 op_sel_hi:[1,0]
	s_waitcnt lgkmcnt(0)
	v_mov_b32_e32 v24, v10
	v_div_scale_f32 v9, s[26:27], v15, v15, 1.0
	v_rcp_f32_e32 v10, v9
	v_mov_b32_e32 v25, v12
	v_fma_f32 v12, -v9, v10, 1.0
	v_fmac_f32_e32 v10, v12, v10
	v_div_scale_f32 v12, vcc, 1.0, v15, 1.0
	v_mul_f32_e32 v16, v12, v10
	v_fma_f32 v17, -v9, v16, v12
	v_fmac_f32_e32 v16, v17, v10
	v_fma_f32 v9, -v9, v16, v12
	v_div_fmas_f32 v9, v9, v10, v16
	v_div_fixup_f32 v27, v9, v15, 1.0
	v_div_scale_f32 v9, s[26:27], v14, v14, 1.0
	v_rcp_f32_e32 v10, v9
	s_nop 0
	v_fma_f32 v12, -v9, v10, 1.0
	v_fmac_f32_e32 v10, v12, v10
	v_div_scale_f32 v12, vcc, 1.0, v14, 1.0
	v_mul_f32_e32 v15, v12, v10
	v_fma_f32 v16, -v9, v15, v12
	v_fmac_f32_e32 v15, v16, v10
	v_fma_f32 v9, -v9, v15, v12
	v_div_fmas_f32 v9, v9, v10, v15
	v_div_fixup_f32 v26, v9, v14, 1.0
	v_mov_b32_e32 v14, v156
	v_mov_b32_e32 v15, v157
	v_mov_b32_e32 v16, v158
	v_mov_b32_e32 v17, v159
	v_mov_b32_e32 v12, v11
	v_mov_b32_e32 v10, v14
	v_mov_b32_e32 v11, v16
	v_pk_fma_f32 v[10:11], v[24:25], v[22:23], v[10:11]
	v_mov_b32_e32 v16, v15
	v_pk_fma_f32 v[12:13], v[12:13], v[26:27], v[16:17]
	v_and_b32_sdwa v9, v11, v95 dst_sel:DWORD dst_unused:UNUSED_PAD src0_sel:WORD_1 src1_sel:DWORD
	v_and_b32_sdwa v14, v10, v95 dst_sel:DWORD dst_unused:UNUSED_PAD src0_sel:WORD_1 src1_sel:DWORD
	v_add3_u32 v10, v10, v14, s39
	v_add3_u32 v9, v11, v9, s39
	v_and_b32_sdwa v11, v13, v95 dst_sel:DWORD dst_unused:UNUSED_PAD src0_sel:WORD_1 src1_sel:DWORD
	v_and_b32_sdwa v14, v12, v95 dst_sel:DWORD dst_unused:UNUSED_PAD src0_sel:WORD_1 src1_sel:DWORD
	v_add3_u32 v11, v13, v11, s39
	v_add3_u32 v12, v12, v14, s39
	v_and_b32_e32 v11, 0xffff0000, v11
	v_and_b32_e32 v12, 0xffff0000, v12
	v_or_b32_sdwa v11, v11, v9 dst_sel:DWORD dst_unused:UNUSED_PAD src0_sel:DWORD src1_sel:WORD_1
	v_or_b32_sdwa v10, v12, v10 dst_sel:DWORD dst_unused:UNUSED_PAD src0_sel:DWORD src1_sel:WORD_1
	v_add_u32_e32 v9, 0x100, v8
	global_store_dwordx2 v[20:21], v[10:11], off
	v_ashrrev_i32_e32 v10, 5, v9
	v_ashrrev_i32_e32 v11, 31, v10
	v_lshl_add_u64 v[12:13], s[40:41], 0, v[10:11]
	v_lshl_or_b32 v9, v10, 9, v152
	v_mad_u64_u32 v[10:11], s[26:27], v12, s22, v[6:7]
	v_mad_i32_i24 v11, v13, s22, v11
	v_lshl_add_u64 v[10:11], v[10:11], 0, v[4:5]
	v_add_co_u32_e32 v10, vcc, s21, v10
	s_nop 1
	v_addc_co_u32_e32 v11, vcc, 0, v11, vcc
	v_mov_b32_e32 v10, v160
	v_mov_b32_e32 v11, v161
	v_lshlrev_b32_e32 v14, 16, v10
	v_and_b32_e32 v10, 0xffff0000, v10
	v_lshlrev_b32_e32 v15, 16, v11
	v_mul_f32_e32 v10, 0xbfb8aa3b, v10
	v_mul_f32_e32 v14, 0xbfb8aa3b, v14
	v_exp_f32_e32 v16, v10
	v_mul_f32_e32 v10, 0xbfb8aa3b, v15
	v_exp_f32_e32 v14, v14
	v_exp_f32_e32 v15, v10
	v_and_b32_e32 v11, 0xffff0000, v11
	v_mul_f32_e32 v10, 0xbfb8aa3b, v11
	v_exp_f32_e32 v17, v10
	v_lshlrev_b64 v[10:11], 12, v[12:13]
	v_lshl_add_u64 v[18:19], v[0:1], 0, v[10:11]
	v_lshlrev_b64 v[10:11], 11, v[12:13]
	v_pk_add_f32 v[14:15], v[14:15], 1.0 op_sel_hi:[1,0]
	v_lshl_add_u64 v[20:21], v[2:3], 0, v[10:11]
	ds_read_b128 v[10:13], v9
	v_div_scale_f32 v9, s[26:27], v15, v15, 1.0
	v_rcp_f32_e32 v22, v9
	s_nop 0
	v_fma_f32 v23, -v9, v22, 1.0
	v_fmac_f32_e32 v22, v23, v22
	v_div_scale_f32 v23, vcc, 1.0, v15, 1.0
	v_mul_f32_e32 v24, v23, v22
	v_fma_f32 v25, -v9, v24, v23
	v_fmac_f32_e32 v24, v25, v22
	v_fma_f32 v9, -v9, v24, v23
	v_div_fmas_f32 v9, v9, v22, v24
	v_div_fixup_f32 v23, v9, v15, 1.0
	v_div_scale_f32 v9, s[26:27], v14, v14, 1.0
	v_rcp_f32_e32 v15, v9
	s_nop 0
	v_fma_f32 v22, -v9, v15, 1.0
	v_fmac_f32_e32 v15, v22, v15
	v_div_scale_f32 v22, vcc, 1.0, v14, 1.0
	v_mul_f32_e32 v24, v22, v15
	v_fma_f32 v25, -v9, v24, v22
	v_fmac_f32_e32 v24, v25, v15
	v_fma_f32 v9, -v9, v24, v22
	v_div_fmas_f32 v9, v9, v15, v24
	v_div_fixup_f32 v22, v9, v14, 1.0
	v_pk_add_f32 v[14:15], v[16:17], 1.0 op_sel_hi:[1,0]
	s_waitcnt lgkmcnt(0)
; DEVI float sigmoidf_(float x) { return 1.f / (1.f + __expf(-x)); }
; template <int BR, int IN, int OUT>
; DEVI void p6_branch(const Params& P, int pm, int pn, float* macc, char* smem, int tid) {
;     ...
; #pragma unroll 8
;   for (int q = 0; q < 16; ++q) {
;     const int id = tid + 256 * q, row = id >> 5, c4 = id & 31;
;     const long grow = (long)pm * 128 + row;
;     const int gcol = pn * 128 + c4 * 4;
;     float4 a = *reinterpret_cast<const float4*>(T + row * 128 + c4 * 4);
;     float g[4];
;     load4bf(Z + grow * NCOL + (9 + BR) * 1024 + gcol, g);
;     float v[4] = {sigmoidf_(g[0]) * a.x, sigmoidf_(g[1]) * a.y, sigmoidf_(g[2]) * a.z, sigmoidf_(g[3]) * a.w};
;     if (IN == 1) {
;       float mo[4]; load4bf(M + grow * 1024 + gcol, mo);
;       v[0] += mo[0]; v[1] += mo[1]; v[2] += mo[2]; v[3] += mo[3];
;     }
;     if (IN == 2) {
;       float4 mo = *reinterpret_cast<const float4*>(macc + grow * 1024 + gcol);
;       v[0] += mo.x; v[1] += mo.y; v[2] += mo.z; v[3] += mo.w;
;     }
;     if (OUT == 1) *reinterpret_cast<float4*>(macc + grow * 1024 + gcol) = make_float4(v[0], v[1], v[2], v[3]);
;     else store4bf(M + grow * 1024 + gcol, v);
;   }
	v_mov_b32_e32 v24, v10
	v_div_scale_f32 v9, s[26:27], v15, v15, 1.0
	v_rcp_f32_e32 v10, v9
	v_mov_b32_e32 v25, v12
	v_fma_f32 v12, -v9, v10, 1.0
	v_fmac_f32_e32 v10, v12, v10
	v_div_scale_f32 v12, vcc, 1.0, v15, 1.0
	v_mul_f32_e32 v16, v12, v10
	v_fma_f32 v17, -v9, v16, v12
	v_fmac_f32_e32 v16, v17, v10
	v_fma_f32 v9, -v9, v16, v12
	v_div_fmas_f32 v9, v9, v10, v16
	v_div_fixup_f32 v27, v9, v15, 1.0
	v_div_scale_f32 v9, s[26:27], v14, v14, 1.0
	v_rcp_f32_e32 v10, v9
	s_nop 0
	v_fma_f32 v12, -v9, v10, 1.0
	v_fmac_f32_e32 v10, v12, v10
	v_div_scale_f32 v12, vcc, 1.0, v14, 1.0
	v_mul_f32_e32 v15, v12, v10
	v_fma_f32 v16, -v9, v15, v12
	v_fmac_f32_e32 v15, v16, v10
	v_fma_f32 v9, -v9, v15, v12
	v_div_fmas_f32 v9, v9, v10, v15
	v_div_fixup_f32 v26, v9, v14, 1.0
	v_mov_b32_e32 v14, v164
	v_mov_b32_e32 v15, v165
	v_mov_b32_e32 v16, v166
	v_mov_b32_e32 v17, v167
	v_mov_b32_e32 v12, v11
	v_mov_b32_e32 v10, v14
	v_mov_b32_e32 v11, v16
	v_pk_fma_f32 v[10:11], v[24:25], v[22:23], v[10:11]
	v_mov_b32_e32 v16, v15
	v_pk_fma_f32 v[12:13], v[12:13], v[26:27], v[16:17]
	v_and_b32_sdwa v9, v11, v95 dst_sel:DWORD dst_unused:UNUSED_PAD src0_sel:WORD_1 src1_sel:DWORD
	v_and_b32_sdwa v14, v10, v95 dst_sel:DWORD dst_unused:UNUSED_PAD src0_sel:WORD_1 src1_sel:DWORD
	v_add3_u32 v10, v10, v14, s39
	v_add3_u32 v9, v11, v9, s39
	v_and_b32_sdwa v11, v13, v95 dst_sel:DWORD dst_unused:UNUSED_PAD src0_sel:WORD_1 src1_sel:DWORD
	v_and_b32_sdwa v14, v12, v95 dst_sel:DWORD dst_unused:UNUSED_PAD src0_sel:WORD_1 src1_sel:DWORD
	v_add3_u32 v11, v13, v11, s39
	v_add3_u32 v12, v12, v14, s39
	v_and_b32_e32 v11, 0xffff0000, v11
	v_and_b32_e32 v12, 0xffff0000, v12
	v_or_b32_sdwa v11, v11, v9 dst_sel:DWORD dst_unused:UNUSED_PAD src0_sel:DWORD src1_sel:WORD_1
	v_or_b32_sdwa v10, v12, v10 dst_sel:DWORD dst_unused:UNUSED_PAD src0_sel:DWORD src1_sel:WORD_1
	v_add_u32_e32 v9, 0x200, v8
	global_store_dwordx2 v[20:21], v[10:11], off
	v_ashrrev_i32_e32 v10, 5, v9
	v_ashrrev_i32_e32 v11, 31, v10
	v_lshl_add_u64 v[12:13], s[40:41], 0, v[10:11]
	v_lshl_or_b32 v9, v10, 9, v152
	v_mad_u64_u32 v[10:11], s[26:27], v12, s22, v[6:7]
	v_mad_i32_i24 v11, v13, s22, v11
	v_lshl_add_u64 v[10:11], v[10:11], 0, v[4:5]
	v_add_co_u32_e32 v10, vcc, s21, v10
	s_nop 1
	v_addc_co_u32_e32 v11, vcc, 0, v11, vcc
	v_mov_b32_e32 v10, v162
	v_mov_b32_e32 v11, v163
	v_lshlrev_b32_e32 v14, 16, v10
	v_and_b32_e32 v10, 0xffff0000, v10
	v_lshlrev_b32_e32 v15, 16, v11
	v_mul_f32_e32 v10, 0xbfb8aa3b, v10
	v_mul_f32_e32 v14, 0xbfb8aa3b, v14
	v_exp_f32_e32 v16, v10
	v_mul_f32_e32 v10, 0xbfb8aa3b, v15
	v_exp_f32_e32 v14, v14
	v_exp_f32_e32 v15, v10
	v_and_b32_e32 v11, 0xffff0000, v11
	v_mul_f32_e32 v10, 0xbfb8aa3b, v11
	v_exp_f32_e32 v17, v10
	v_lshlrev_b64 v[10:11], 12, v[12:13]
	v_lshl_add_u64 v[18:19], v[0:1], 0, v[10:11]
	v_lshlrev_b64 v[10:11], 11, v[12:13]
	v_pk_add_f32 v[14:15], v[14:15], 1.0 op_sel_hi:[1,0]
	v_lshl_add_u64 v[20:21], v[2:3], 0, v[10:11]
	ds_read_b128 v[10:13], v9
	v_div_scale_f32 v9, s[26:27], v15, v15, 1.0
	v_rcp_f32_e32 v22, v9
	s_nop 0
	v_fma_f32 v23, -v9, v22, 1.0
	v_fmac_f32_e32 v22, v23, v22
	v_div_scale_f32 v23, vcc, 1.0, v15, 1.0
	v_mul_f32_e32 v24, v23, v22
	v_fma_f32 v25, -v9, v24, v23
	v_fmac_f32_e32 v24, v25, v22
	v_fma_f32 v9, -v9, v24, v23
	v_div_fmas_f32 v9, v9, v22, v24
	v_div_fixup_f32 v23, v9, v15, 1.0
	v_div_scale_f32 v9, s[26:27], v14, v14, 1.0
	v_rcp_f32_e32 v15, v9
	s_nop 0
	v_fma_f32 v22, -v9, v15, 1.0
	v_fmac_f32_e32 v15, v22, v15
	v_div_scale_f32 v22, vcc, 1.0, v14, 1.0
	v_mul_f32_e32 v24, v22, v15
	v_fma_f32 v25, -v9, v24, v22
	v_fmac_f32_e32 v24, v25, v15
	v_fma_f32 v9, -v9, v24, v22
	v_div_fmas_f32 v9, v9, v15, v24
	v_div_fixup_f32 v22, v9, v14, 1.0
	v_pk_add_f32 v[14:15], v[16:17], 1.0 op_sel_hi:[1,0]
	s_waitcnt lgkmcnt(0)
	v_mov_b32_e32 v24, v10
	v_div_scale_f32 v9, s[26:27], v15, v15, 1.0
	v_rcp_f32_e32 v10, v9
	v_mov_b32_e32 v25, v12
	v_fma_f32 v12, -v9, v10, 1.0
	v_fmac_f32_e32 v10, v12, v10
	v_div_scale_f32 v12, vcc, 1.0, v15, 1.0
	v_mul_f32_e32 v16, v12, v10
	v_fma_f32 v17, -v9, v16, v12
	v_fmac_f32_e32 v16, v17, v10
	v_fma_f32 v9, -v9, v16, v12
	v_div_fmas_f32 v9, v9, v10, v16
	v_div_fixup_f32 v27, v9, v15, 1.0
	v_div_scale_f32 v9, s[26:27], v14, v14, 1.0
	v_rcp_f32_e32 v10, v9
	s_nop 0
	v_fma_f32 v12, -v9, v10, 1.0
	v_fmac_f32_e32 v10, v12, v10
	v_div_scale_f32 v12, vcc, 1.0, v14, 1.0
	v_mul_f32_e32 v15, v12, v10
	v_fma_f32 v16, -v9, v15, v12
	v_fmac_f32_e32 v15, v16, v10
	v_fma_f32 v9, -v9, v15, v12
	v_div_fmas_f32 v9, v9, v10, v15
	v_div_fixup_f32 v26, v9, v14, 1.0
	v_mov_b32_e32 v14, v168
	v_mov_b32_e32 v15, v169
	v_mov_b32_e32 v16, v170
	v_mov_b32_e32 v17, v171
	v_mov_b32_e32 v12, v11
	v_mov_b32_e32 v10, v14
	v_mov_b32_e32 v11, v16
	v_pk_fma_f32 v[10:11], v[24:25], v[22:23], v[10:11]
	v_mov_b32_e32 v16, v15
	v_pk_fma_f32 v[12:13], v[12:13], v[26:27], v[16:17]
	v_and_b32_sdwa v9, v11, v95 dst_sel:DWORD dst_unused:UNUSED_PAD src0_sel:WORD_1 src1_sel:DWORD
	v_and_b32_sdwa v14, v10, v95 dst_sel:DWORD dst_unused:UNUSED_PAD src0_sel:WORD_1 src1_sel:DWORD
	v_add3_u32 v10, v10, v14, s39
	v_add3_u32 v9, v11, v9, s39
	v_and_b32_sdwa v11, v13, v95 dst_sel:DWORD dst_unused:UNUSED_PAD src0_sel:WORD_1 src1_sel:DWORD
	v_and_b32_sdwa v14, v12, v95 dst_sel:DWORD dst_unused:UNUSED_PAD src0_sel:WORD_1 src1_sel:DWORD
	v_add3_u32 v11, v13, v11, s39
	v_add3_u32 v12, v12, v14, s39
	v_and_b32_e32 v11, 0xffff0000, v11
	v_and_b32_e32 v12, 0xffff0000, v12
	v_or_b32_sdwa v11, v11, v9 dst_sel:DWORD dst_unused:UNUSED_PAD src0_sel:DWORD src1_sel:WORD_1
	v_or_b32_sdwa v10, v12, v10 dst_sel:DWORD dst_unused:UNUSED_PAD src0_sel:DWORD src1_sel:WORD_1
	v_add_u32_e32 v9, 0x300, v8
; DEVI float sigmoidf_(float x) { return 1.f / (1.f + __expf(-x)); }
; template <int BR, int IN, int OUT>
; DEVI void p6_branch(const Params& P, int pm, int pn, float* macc, char* smem, int tid) {
;     ...
; #pragma unroll 8
;   for (int q = 0; q < 16; ++q) {
;     const int id = tid + 256 * q, row = id >> 5, c4 = id & 31;
;     const long grow = (long)pm * 128 + row;
;     const int gcol = pn * 128 + c4 * 4;
;     float4 a = *reinterpret_cast<const float4*>(T + row * 128 + c4 * 4);
;     float g[4];
;     load4bf(Z + grow * NCOL + (9 + BR) * 1024 + gcol, g);
;     float v[4] = {sigmoidf_(g[0]) * a.x, sigmoidf_(g[1]) * a.y, sigmoidf_(g[2]) * a.z, sigmoidf_(g[3]) * a.w};
;     if (IN == 1) {
;       float mo[4]; load4bf(M + grow * 1024 + gcol, mo);
;       v[0] += mo[0]; v[1] += mo[1]; v[2] += mo[2]; v[3] += mo[3];
;     }
;     if (IN == 2) {
;       float4 mo = *reinterpret_cast<const float4*>(macc + grow * 1024 + gcol);
;       v[0] += mo.x; v[1] += mo.y; v[2] += mo.z; v[3] += mo.w;
;     }
;     if (OUT == 1) *reinterpret_cast<float4*>(macc + grow * 1024 + gcol) = make_float4(v[0], v[1], v[2], v[3]);
;     else store4bf(M + grow * 1024 + gcol, v);
;   }
	global_store_dwordx2 v[20:21], v[10:11], off
	v_ashrrev_i32_e32 v10, 5, v9
	v_ashrrev_i32_e32 v11, 31, v10
	v_lshl_add_u64 v[12:13], s[40:41], 0, v[10:11]
	v_lshl_or_b32 v9, v10, 9, v152
	v_mad_u64_u32 v[10:11], s[26:27], v12, s22, v[6:7]
	v_mad_i32_i24 v11, v13, s22, v11
	v_lshl_add_u64 v[10:11], v[10:11], 0, v[4:5]
	v_add_co_u32_e32 v10, vcc, s21, v10
	s_nop 1
	v_addc_co_u32_e32 v11, vcc, 0, v11, vcc
	v_mov_b32_e32 v10, v172
	v_mov_b32_e32 v11, v173
	v_lshlrev_b32_e32 v14, 16, v10
	v_and_b32_e32 v10, 0xffff0000, v10
	v_lshlrev_b32_e32 v15, 16, v11
	v_mul_f32_e32 v10, 0xbfb8aa3b, v10
	v_mul_f32_e32 v14, 0xbfb8aa3b, v14
	v_exp_f32_e32 v16, v10
	v_mul_f32_e32 v10, 0xbfb8aa3b, v15
	v_exp_f32_e32 v14, v14
	v_exp_f32_e32 v15, v10
	v_and_b32_e32 v11, 0xffff0000, v11
	v_mul_f32_e32 v10, 0xbfb8aa3b, v11
	v_exp_f32_e32 v17, v10
	v_lshlrev_b64 v[10:11], 12, v[12:13]
	v_lshl_add_u64 v[18:19], v[0:1], 0, v[10:11]
	v_lshlrev_b64 v[10:11], 11, v[12:13]
	v_pk_add_f32 v[14:15], v[14:15], 1.0 op_sel_hi:[1,0]
	v_lshl_add_u64 v[20:21], v[2:3], 0, v[10:11]
	ds_read_b128 v[10:13], v9
	v_div_scale_f32 v9, s[26:27], v15, v15, 1.0
	v_rcp_f32_e32 v22, v9
	s_nop 0
	v_fma_f32 v23, -v9, v22, 1.0
	v_fmac_f32_e32 v22, v23, v22
	v_div_scale_f32 v23, vcc, 1.0, v15, 1.0
	v_mul_f32_e32 v24, v23, v22
	v_fma_f32 v25, -v9, v24, v23
	v_fmac_f32_e32 v24, v25, v22
	v_fma_f32 v9, -v9, v24, v23
	v_div_fmas_f32 v9, v9, v22, v24
	v_div_fixup_f32 v23, v9, v15, 1.0
	v_div_scale_f32 v9, s[26:27], v14, v14, 1.0
	v_rcp_f32_e32 v15, v9
	s_nop 0
	v_fma_f32 v22, -v9, v15, 1.0
	v_fmac_f32_e32 v15, v22, v15
	v_div_scale_f32 v22, vcc, 1.0, v14, 1.0
	v_mul_f32_e32 v24, v22, v15
	v_fma_f32 v25, -v9, v24, v22
	v_fmac_f32_e32 v24, v25, v15
	v_fma_f32 v9, -v9, v24, v22
	v_div_fmas_f32 v9, v9, v15, v24
	v_div_fixup_f32 v22, v9, v14, 1.0
	v_pk_add_f32 v[14:15], v[16:17], 1.0 op_sel_hi:[1,0]
	s_waitcnt lgkmcnt(0)
	v_mov_b32_e32 v24, v10
	v_div_scale_f32 v9, s[26:27], v15, v15, 1.0
	v_rcp_f32_e32 v10, v9
	v_mov_b32_e32 v25, v12
	v_fma_f32 v12, -v9, v10, 1.0
	v_fmac_f32_e32 v10, v12, v10
	v_div_scale_f32 v12, vcc, 1.0, v15, 1.0
	v_mul_f32_e32 v16, v12, v10
	v_fma_f32 v17, -v9, v16, v12
	v_fmac_f32_e32 v16, v17, v10
	v_fma_f32 v9, -v9, v16, v12
	v_div_fmas_f32 v9, v9, v10, v16
	v_div_fixup_f32 v27, v9, v15, 1.0
	v_div_scale_f32 v9, s[26:27], v14, v14, 1.0
	v_rcp_f32_e32 v10, v9
	s_nop 0
	v_fma_f32 v12, -v9, v10, 1.0
	v_fmac_f32_e32 v10, v12, v10
	v_div_scale_f32 v12, vcc, 1.0, v14, 1.0
	v_mul_f32_e32 v15, v12, v10
	v_fma_f32 v16, -v9, v15, v12
	v_fmac_f32_e32 v15, v16, v10
	v_fma_f32 v9, -v9, v15, v12
	v_div_fmas_f32 v9, v9, v10, v15
	v_div_fixup_f32 v26, v9, v14, 1.0
	v_mov_b32_e32 v14, v176
	v_mov_b32_e32 v15, v177
	v_mov_b32_e32 v16, v178
	v_mov_b32_e32 v17, v179
	v_mov_b32_e32 v12, v11
	v_mov_b32_e32 v10, v14
	v_mov_b32_e32 v11, v16
	v_pk_fma_f32 v[10:11], v[24:25], v[22:23], v[10:11]
	v_mov_b32_e32 v16, v15
	v_pk_fma_f32 v[12:13], v[12:13], v[26:27], v[16:17]
	v_and_b32_sdwa v9, v11, v95 dst_sel:DWORD dst_unused:UNUSED_PAD src0_sel:WORD_1 src1_sel:DWORD
	v_and_b32_sdwa v14, v10, v95 dst_sel:DWORD dst_unused:UNUSED_PAD src0_sel:WORD_1 src1_sel:DWORD
	v_add3_u32 v10, v10, v14, s39
	v_add3_u32 v9, v11, v9, s39
	v_and_b32_sdwa v11, v13, v95 dst_sel:DWORD dst_unused:UNUSED_PAD src0_sel:WORD_1 src1_sel:DWORD
	v_and_b32_sdwa v14, v12, v95 dst_sel:DWORD dst_unused:UNUSED_PAD src0_sel:WORD_1 src1_sel:DWORD
	v_add3_u32 v11, v13, v11, s39
	v_add3_u32 v12, v12, v14, s39
	v_and_b32_e32 v11, 0xffff0000, v11
	v_and_b32_e32 v12, 0xffff0000, v12
	v_or_b32_sdwa v11, v11, v9 dst_sel:DWORD dst_unused:UNUSED_PAD src0_sel:DWORD src1_sel:WORD_1
	v_or_b32_sdwa v10, v12, v10 dst_sel:DWORD dst_unused:UNUSED_PAD src0_sel:DWORD src1_sel:WORD_1
	v_add_u32_e32 v9, 0x400, v8
	global_store_dwordx2 v[20:21], v[10:11], off
	v_ashrrev_i32_e32 v10, 5, v9
	v_ashrrev_i32_e32 v11, 31, v10
	v_lshl_add_u64 v[12:13], s[40:41], 0, v[10:11]
	v_lshl_or_b32 v9, v10, 9, v152
	v_mad_u64_u32 v[10:11], s[26:27], v12, s22, v[6:7]
	v_mad_i32_i24 v11, v13, s22, v11
	v_lshl_add_u64 v[10:11], v[10:11], 0, v[4:5]
	v_add_co_u32_e32 v10, vcc, s21, v10
	s_nop 1
	v_addc_co_u32_e32 v11, vcc, 0, v11, vcc
	v_mov_b32_e32 v10, v174
	v_mov_b32_e32 v11, v175
	v_lshlrev_b32_e32 v14, 16, v10
	v_and_b32_e32 v10, 0xffff0000, v10
	v_lshlrev_b32_e32 v15, 16, v11
	v_mul_f32_e32 v10, 0xbfb8aa3b, v10
	v_mul_f32_e32 v14, 0xbfb8aa3b, v14
	v_exp_f32_e32 v16, v10
	v_mul_f32_e32 v10, 0xbfb8aa3b, v15
	v_exp_f32_e32 v14, v14
	v_exp_f32_e32 v15, v10
	v_and_b32_e32 v11, 0xffff0000, v11
	v_mul_f32_e32 v10, 0xbfb8aa3b, v11
	v_exp_f32_e32 v17, v10
	v_lshlrev_b64 v[10:11], 12, v[12:13]
	v_lshl_add_u64 v[18:19], v[0:1], 0, v[10:11]
	v_lshlrev_b64 v[10:11], 11, v[12:13]
	v_pk_add_f32 v[14:15], v[14:15], 1.0 op_sel_hi:[1,0]
	v_lshl_add_u64 v[20:21], v[2:3], 0, v[10:11]
	ds_read_b128 v[10:13], v9
	v_div_scale_f32 v9, s[26:27], v15, v15, 1.0
	v_rcp_f32_e32 v22, v9
	s_nop 0
	v_fma_f32 v23, -v9, v22, 1.0
	v_fmac_f32_e32 v22, v23, v22
	v_div_scale_f32 v23, vcc, 1.0, v15, 1.0
	v_mul_f32_e32 v24, v23, v22
	v_fma_f32 v25, -v9, v24, v23
	v_fmac_f32_e32 v24, v25, v22
	v_fma_f32 v9, -v9, v24, v23
	v_div_fmas_f32 v9, v9, v22, v24
	v_div_fixup_f32 v23, v9, v15, 1.0
	v_div_scale_f32 v9, s[26:27], v14, v14, 1.0
	v_rcp_f32_e32 v15, v9
	s_nop 0
	v_fma_f32 v22, -v9, v15, 1.0
	v_fmac_f32_e32 v15, v22, v15
	v_div_scale_f32 v22, vcc, 1.0, v14, 1.0
	v_mul_f32_e32 v24, v22, v15
	v_fma_f32 v25, -v9, v24, v22
	v_fmac_f32_e32 v24, v25, v15
	v_fma_f32 v9, -v9, v24, v22
	v_div_fmas_f32 v9, v9, v15, v24
	v_div_fixup_f32 v22, v9, v14, 1.0
	v_pk_add_f32 v[14:15], v[16:17], 1.0 op_sel_hi:[1,0]
	s_waitcnt lgkmcnt(0)
; DEVI float sigmoidf_(float x) { return 1.f / (1.f + __expf(-x)); }
; template <int BR, int IN, int OUT>
; DEVI void p6_branch(const Params& P, int pm, int pn, float* macc, char* smem, int tid) {
;     ...
; #pragma unroll 8
;   for (int q = 0; q < 16; ++q) {
;     const int id = tid + 256 * q, row = id >> 5, c4 = id & 31;
;     const long grow = (long)pm * 128 + row;
;     const int gcol = pn * 128 + c4 * 4;
;     float4 a = *reinterpret_cast<const float4*>(T + row * 128 + c4 * 4);
;     float g[4];
;     load4bf(Z + grow * NCOL + (9 + BR) * 1024 + gcol, g);
;     float v[4] = {sigmoidf_(g[0]) * a.x, sigmoidf_(g[1]) * a.y, sigmoidf_(g[2]) * a.z, sigmoidf_(g[3]) * a.w};
;     if (IN == 1) {
;       float mo[4]; load4bf(M + grow * 1024 + gcol, mo);
;       v[0] += mo[0]; v[1] += mo[1]; v[2] += mo[2]; v[3] += mo[3];
;     }
;     if (IN == 2) {
;       float4 mo = *reinterpret_cast<const float4*>(macc + grow * 1024 + gcol);
;       v[0] += mo.x; v[1] += mo.y; v[2] += mo.z; v[3] += mo.w;
;     }
;     if (OUT == 1) *reinterpret_cast<float4*>(macc + grow * 1024 + gcol) = make_float4(v[0], v[1], v[2], v[3]);
;     else store4bf(M + grow * 1024 + gcol, v);
;   }
	v_mov_b32_e32 v24, v10
	v_div_scale_f32 v9, s[26:27], v15, v15, 1.0
	v_rcp_f32_e32 v10, v9
	v_mov_b32_e32 v25, v12
	v_fma_f32 v12, -v9, v10, 1.0
	v_fmac_f32_e32 v10, v12, v10
	v_div_scale_f32 v12, vcc, 1.0, v15, 1.0
	v_mul_f32_e32 v16, v12, v10
	v_fma_f32 v17, -v9, v16, v12
	v_fmac_f32_e32 v16, v17, v10
	v_fma_f32 v9, -v9, v16, v12
	v_div_fmas_f32 v9, v9, v10, v16
	v_div_fixup_f32 v27, v9, v15, 1.0
	v_div_scale_f32 v9, s[26:27], v14, v14, 1.0
	v_rcp_f32_e32 v10, v9
	s_nop 0
	v_fma_f32 v12, -v9, v10, 1.0
	v_fmac_f32_e32 v10, v12, v10
	v_div_scale_f32 v12, vcc, 1.0, v14, 1.0
	v_mul_f32_e32 v15, v12, v10
	v_fma_f32 v16, -v9, v15, v12
	v_fmac_f32_e32 v15, v16, v10
	v_fma_f32 v9, -v9, v15, v12
	v_div_fmas_f32 v9, v9, v10, v15
	v_div_fixup_f32 v26, v9, v14, 1.0
	v_mov_b32_e32 v14, v180
	v_mov_b32_e32 v15, v181
	v_mov_b32_e32 v16, v182
	v_mov_b32_e32 v17, v183
	v_mov_b32_e32 v12, v11
	v_mov_b32_e32 v10, v14
	v_mov_b32_e32 v11, v16
	v_pk_fma_f32 v[10:11], v[24:25], v[22:23], v[10:11]
	v_mov_b32_e32 v16, v15
	v_pk_fma_f32 v[12:13], v[12:13], v[26:27], v[16:17]
	v_and_b32_sdwa v9, v11, v95 dst_sel:DWORD dst_unused:UNUSED_PAD src0_sel:WORD_1 src1_sel:DWORD
	v_and_b32_sdwa v14, v10, v95 dst_sel:DWORD dst_unused:UNUSED_PAD src0_sel:WORD_1 src1_sel:DWORD
	v_add3_u32 v10, v10, v14, s39
	v_add3_u32 v9, v11, v9, s39
	v_and_b32_sdwa v11, v13, v95 dst_sel:DWORD dst_unused:UNUSED_PAD src0_sel:WORD_1 src1_sel:DWORD
	v_and_b32_sdwa v14, v12, v95 dst_sel:DWORD dst_unused:UNUSED_PAD src0_sel:WORD_1 src1_sel:DWORD
	v_add3_u32 v11, v13, v11, s39
	v_add3_u32 v12, v12, v14, s39
	v_and_b32_e32 v11, 0xffff0000, v11
	v_and_b32_e32 v12, 0xffff0000, v12
	v_or_b32_sdwa v11, v11, v9 dst_sel:DWORD dst_unused:UNUSED_PAD src0_sel:DWORD src1_sel:WORD_1
	v_or_b32_sdwa v10, v12, v10 dst_sel:DWORD dst_unused:UNUSED_PAD src0_sel:DWORD src1_sel:WORD_1
	v_add_u32_e32 v9, 0x500, v8
	global_store_dwordx2 v[20:21], v[10:11], off
	v_ashrrev_i32_e32 v10, 5, v9
	v_ashrrev_i32_e32 v11, 31, v10
	v_lshl_add_u64 v[12:13], s[40:41], 0, v[10:11]
	v_lshl_or_b32 v9, v10, 9, v152
	v_mad_u64_u32 v[10:11], s[26:27], v12, s22, v[6:7]
	v_mad_i32_i24 v11, v13, s22, v11
	v_lshl_add_u64 v[10:11], v[10:11], 0, v[4:5]
	v_add_co_u32_e32 v10, vcc, s21, v10
	s_nop 1
	v_addc_co_u32_e32 v11, vcc, 0, v11, vcc
	v_mov_b32_e32 v10, v208
	v_mov_b32_e32 v11, v209
	v_lshlrev_b32_e32 v14, 16, v10
	v_and_b32_e32 v10, 0xffff0000, v10
	v_lshlrev_b32_e32 v15, 16, v11
	v_mul_f32_e32 v10, 0xbfb8aa3b, v10
	v_mul_f32_e32 v14, 0xbfb8aa3b, v14
	v_exp_f32_e32 v16, v10
	v_mul_f32_e32 v10, 0xbfb8aa3b, v15
	v_exp_f32_e32 v14, v14
	v_exp_f32_e32 v15, v10
	v_and_b32_e32 v11, 0xffff0000, v11
	v_mul_f32_e32 v10, 0xbfb8aa3b, v11
	v_exp_f32_e32 v17, v10
	v_lshlrev_b64 v[10:11], 12, v[12:13]
	v_lshl_add_u64 v[18:19], v[0:1], 0, v[10:11]
	v_lshlrev_b64 v[10:11], 11, v[12:13]
	v_pk_add_f32 v[14:15], v[14:15], 1.0 op_sel_hi:[1,0]
	v_lshl_add_u64 v[20:21], v[2:3], 0, v[10:11]
	ds_read_b128 v[10:13], v9
	v_div_scale_f32 v9, s[26:27], v15, v15, 1.0
	v_rcp_f32_e32 v22, v9
	s_nop 0
	v_fma_f32 v23, -v9, v22, 1.0
	v_fmac_f32_e32 v22, v23, v22
	v_div_scale_f32 v23, vcc, 1.0, v15, 1.0
	v_mul_f32_e32 v24, v23, v22
	v_fma_f32 v25, -v9, v24, v23
	v_fmac_f32_e32 v24, v25, v22
	v_fma_f32 v9, -v9, v24, v23
	v_div_fmas_f32 v9, v9, v22, v24
	v_div_fixup_f32 v23, v9, v15, 1.0
	v_div_scale_f32 v9, s[26:27], v14, v14, 1.0
	v_rcp_f32_e32 v15, v9
	s_nop 0
	v_fma_f32 v22, -v9, v15, 1.0
	v_fmac_f32_e32 v15, v22, v15
	v_div_scale_f32 v22, vcc, 1.0, v14, 1.0
	v_mul_f32_e32 v24, v22, v15
	v_fma_f32 v25, -v9, v24, v22
	v_fmac_f32_e32 v24, v25, v15
	v_fma_f32 v9, -v9, v24, v22
	v_div_fmas_f32 v9, v9, v15, v24
	v_div_fixup_f32 v22, v9, v14, 1.0
	v_pk_add_f32 v[14:15], v[16:17], 1.0 op_sel_hi:[1,0]
	s_waitcnt lgkmcnt(0)
	v_mov_b32_e32 v24, v10
	v_div_scale_f32 v9, s[26:27], v15, v15, 1.0
	v_rcp_f32_e32 v10, v9
	v_mov_b32_e32 v25, v12
	v_fma_f32 v12, -v9, v10, 1.0
	v_fmac_f32_e32 v10, v12, v10
	v_div_scale_f32 v12, vcc, 1.0, v15, 1.0
	v_mul_f32_e32 v16, v12, v10
	v_fma_f32 v17, -v9, v16, v12
	v_fmac_f32_e32 v16, v17, v10
	v_fma_f32 v9, -v9, v16, v12
	v_div_fmas_f32 v9, v9, v10, v16
	v_div_fixup_f32 v27, v9, v15, 1.0
	v_div_scale_f32 v9, s[26:27], v14, v14, 1.0
	v_rcp_f32_e32 v10, v9
	s_nop 0
	v_fma_f32 v12, -v9, v10, 1.0
	v_fmac_f32_e32 v10, v12, v10
	v_div_scale_f32 v12, vcc, 1.0, v14, 1.0
	v_mul_f32_e32 v15, v12, v10
	v_fma_f32 v16, -v9, v15, v12
	v_fmac_f32_e32 v15, v16, v10
	v_fma_f32 v9, -v9, v15, v12
	v_div_fmas_f32 v9, v9, v10, v15
	v_div_fixup_f32 v26, v9, v14, 1.0
	v_mov_b32_e32 v14, v212
	v_mov_b32_e32 v15, v213
	v_mov_b32_e32 v16, v214
	v_mov_b32_e32 v17, v215
	v_mov_b32_e32 v12, v11
	v_mov_b32_e32 v10, v14
	v_mov_b32_e32 v11, v16
	v_pk_fma_f32 v[10:11], v[24:25], v[22:23], v[10:11]
	v_mov_b32_e32 v16, v15
	v_pk_fma_f32 v[12:13], v[12:13], v[26:27], v[16:17]
	v_and_b32_sdwa v9, v11, v95 dst_sel:DWORD dst_unused:UNUSED_PAD src0_sel:WORD_1 src1_sel:DWORD
	v_and_b32_sdwa v14, v10, v95 dst_sel:DWORD dst_unused:UNUSED_PAD src0_sel:WORD_1 src1_sel:DWORD
	v_add3_u32 v10, v10, v14, s39
	v_add3_u32 v9, v11, v9, s39
	v_and_b32_sdwa v11, v13, v95 dst_sel:DWORD dst_unused:UNUSED_PAD src0_sel:WORD_1 src1_sel:DWORD
	v_and_b32_sdwa v14, v12, v95 dst_sel:DWORD dst_unused:UNUSED_PAD src0_sel:WORD_1 src1_sel:DWORD
	v_add3_u32 v11, v13, v11, s39
	v_add3_u32 v12, v12, v14, s39
	v_and_b32_e32 v11, 0xffff0000, v11
	v_and_b32_e32 v12, 0xffff0000, v12
	v_or_b32_sdwa v11, v11, v9 dst_sel:DWORD dst_unused:UNUSED_PAD src0_sel:DWORD src1_sel:WORD_1
	v_or_b32_sdwa v10, v12, v10 dst_sel:DWORD dst_unused:UNUSED_PAD src0_sel:DWORD src1_sel:WORD_1
	v_add_u32_e32 v9, 0x600, v8
; DEVI float sigmoidf_(float x) { return 1.f / (1.f + __expf(-x)); }
; template <int BR, int IN, int OUT>
; DEVI void p6_branch(const Params& P, int pm, int pn, float* macc, char* smem, int tid) {
;     ...
; #pragma unroll 8
;   for (int q = 0; q < 16; ++q) {
;     const int id = tid + 256 * q, row = id >> 5, c4 = id & 31;
;     const long grow = (long)pm * 128 + row;
;     const int gcol = pn * 128 + c4 * 4;
;     float4 a = *reinterpret_cast<const float4*>(T + row * 128 + c4 * 4);
;     float g[4];
;     load4bf(Z + grow * NCOL + (9 + BR) * 1024 + gcol, g);
;     float v[4] = {sigmoidf_(g[0]) * a.x, sigmoidf_(g[1]) * a.y, sigmoidf_(g[2]) * a.z, sigmoidf_(g[3]) * a.w};
;     if (IN == 1) {
;       float mo[4]; load4bf(M + grow * 1024 + gcol, mo);
;       v[0] += mo[0]; v[1] += mo[1]; v[2] += mo[2]; v[3] += mo[3];
;     }
;     if (IN == 2) {
;       float4 mo = *reinterpret_cast<const float4*>(macc + grow * 1024 + gcol);
;       v[0] += mo.x; v[1] += mo.y; v[2] += mo.z; v[3] += mo.w;
;     }
;     if (OUT == 1) *reinterpret_cast<float4*>(macc + grow * 1024 + gcol) = make_float4(v[0], v[1], v[2], v[3]);
;     else store4bf(M + grow * 1024 + gcol, v);
;   }
	global_store_dwordx2 v[20:21], v[10:11], off
	v_ashrrev_i32_e32 v10, 5, v9
	v_ashrrev_i32_e32 v11, 31, v10
	v_lshl_add_u64 v[12:13], s[40:41], 0, v[10:11]
	v_lshl_or_b32 v9, v10, 9, v152
	v_mad_u64_u32 v[10:11], s[26:27], v12, s22, v[6:7]
	v_mad_i32_i24 v11, v13, s22, v11
	v_lshl_add_u64 v[10:11], v[10:11], 0, v[4:5]
	v_add_co_u32_e32 v10, vcc, s21, v10
	v_add_u32_e32 v8, 0x700, v8
	s_nop 0
	v_addc_co_u32_e32 v11, vcc, 0, v11, vcc
	v_mov_b32_e32 v10, v210
	v_mov_b32_e32 v11, v211
	v_ashrrev_i32_e32 v8, 5, v8
	v_lshlrev_b32_e32 v14, 16, v10
	v_and_b32_e32 v10, 0xffff0000, v10
	v_lshlrev_b32_e32 v15, 16, v11
	v_mul_f32_e32 v10, 0xbfb8aa3b, v10
	v_mul_f32_e32 v14, 0xbfb8aa3b, v14
	v_exp_f32_e32 v16, v10
	v_mul_f32_e32 v10, 0xbfb8aa3b, v15
	v_exp_f32_e32 v14, v14
	v_exp_f32_e32 v15, v10
	v_and_b32_e32 v11, 0xffff0000, v11
	v_mul_f32_e32 v10, 0xbfb8aa3b, v11
	v_exp_f32_e32 v17, v10
	v_lshlrev_b64 v[10:11], 12, v[12:13]
	v_lshl_add_u64 v[18:19], v[0:1], 0, v[10:11]
	v_lshlrev_b64 v[10:11], 11, v[12:13]
	v_pk_add_f32 v[14:15], v[14:15], 1.0 op_sel_hi:[1,0]
	v_lshl_add_u64 v[20:21], v[2:3], 0, v[10:11]
	ds_read_b128 v[10:13], v9
	v_div_scale_f32 v9, s[26:27], v15, v15, 1.0
	v_rcp_f32_e32 v22, v9
	s_nop 0
	v_fma_f32 v23, -v9, v22, 1.0
	v_fmac_f32_e32 v22, v23, v22
	v_div_scale_f32 v23, vcc, 1.0, v15, 1.0
	v_mul_f32_e32 v24, v23, v22
	v_fma_f32 v25, -v9, v24, v23
	v_fmac_f32_e32 v24, v25, v22
	v_fma_f32 v9, -v9, v24, v23
	v_div_fmas_f32 v9, v9, v22, v24
	v_div_fixup_f32 v23, v9, v15, 1.0
	v_div_scale_f32 v9, s[26:27], v14, v14, 1.0
	v_rcp_f32_e32 v15, v9
	s_nop 0
	v_fma_f32 v22, -v9, v15, 1.0
	v_fmac_f32_e32 v15, v22, v15
	v_div_scale_f32 v22, vcc, 1.0, v14, 1.0
	v_mul_f32_e32 v24, v22, v15
	v_fma_f32 v25, -v9, v24, v22
	v_fmac_f32_e32 v24, v25, v15
	v_fma_f32 v9, -v9, v24, v22
	v_div_fmas_f32 v9, v9, v15, v24
	v_div_fixup_f32 v22, v9, v14, 1.0
	v_pk_add_f32 v[14:15], v[16:17], 1.0 op_sel_hi:[1,0]
	s_waitcnt lgkmcnt(0)
	v_mov_b32_e32 v24, v10
	v_div_scale_f32 v9, s[26:27], v15, v15, 1.0
	v_rcp_f32_e32 v10, v9
	v_mov_b32_e32 v25, v12
	v_fma_f32 v12, -v9, v10, 1.0
	v_fmac_f32_e32 v10, v12, v10
	v_div_scale_f32 v12, vcc, 1.0, v15, 1.0
	v_mul_f32_e32 v16, v12, v10
	v_fma_f32 v17, -v9, v16, v12
	v_fmac_f32_e32 v16, v17, v10
	v_fma_f32 v9, -v9, v16, v12
	v_div_fmas_f32 v9, v9, v10, v16
	v_div_fixup_f32 v27, v9, v15, 1.0
	v_div_scale_f32 v9, s[26:27], v14, v14, 1.0
	v_rcp_f32_e32 v10, v9
	s_nop 0
	v_fma_f32 v12, -v9, v10, 1.0
	v_fmac_f32_e32 v10, v12, v10
	v_div_scale_f32 v12, vcc, 1.0, v14, 1.0
	v_mul_f32_e32 v15, v12, v10
	v_fma_f32 v16, -v9, v15, v12
	v_fmac_f32_e32 v15, v16, v10
	v_fma_f32 v9, -v9, v15, v12
	v_div_fmas_f32 v9, v9, v10, v15
	v_div_fixup_f32 v26, v9, v14, 1.0
	v_mov_b32_e32 v14, v216
	v_mov_b32_e32 v15, v217
	v_mov_b32_e32 v16, v218
	v_mov_b32_e32 v17, v219
	v_mov_b32_e32 v12, v11
	v_mov_b32_e32 v10, v14
	v_mov_b32_e32 v11, v16
	v_pk_fma_f32 v[10:11], v[24:25], v[22:23], v[10:11]
	v_mov_b32_e32 v16, v15
	v_pk_fma_f32 v[12:13], v[12:13], v[26:27], v[16:17]
	v_and_b32_sdwa v9, v11, v95 dst_sel:DWORD dst_unused:UNUSED_PAD src0_sel:WORD_1 src1_sel:DWORD
	v_and_b32_sdwa v14, v10, v95 dst_sel:DWORD dst_unused:UNUSED_PAD src0_sel:WORD_1 src1_sel:DWORD
	v_add3_u32 v10, v10, v14, s39
	v_add3_u32 v9, v11, v9, s39
	v_and_b32_sdwa v11, v13, v95 dst_sel:DWORD dst_unused:UNUSED_PAD src0_sel:WORD_1 src1_sel:DWORD
	v_and_b32_sdwa v14, v12, v95 dst_sel:DWORD dst_unused:UNUSED_PAD src0_sel:WORD_1 src1_sel:DWORD
	v_add3_u32 v11, v13, v11, s39
	v_add3_u32 v12, v12, v14, s39
	v_and_b32_e32 v11, 0xffff0000, v11
	v_and_b32_e32 v12, 0xffff0000, v12
	v_or_b32_sdwa v11, v11, v9 dst_sel:DWORD dst_unused:UNUSED_PAD src0_sel:DWORD src1_sel:WORD_1
	v_or_b32_sdwa v10, v12, v10 dst_sel:DWORD dst_unused:UNUSED_PAD src0_sel:DWORD src1_sel:WORD_1
	v_ashrrev_i32_e32 v9, 31, v8
	global_store_dwordx2 v[20:21], v[10:11], off
	v_lshl_add_u64 v[10:11], s[40:41], 0, v[8:9]
	v_mad_u64_u32 v[6:7], s[26:27], v10, s22, v[6:7]
	v_mad_i32_i24 v7, v11, s22, v7
	v_lshl_add_u64 v[6:7], v[6:7], 0, v[4:5]
	v_add_co_u32_e32 v6, vcc, s21, v6
	v_lshl_or_b32 v8, v8, 9, v152
	s_nop 0
	v_addc_co_u32_e32 v7, vcc, 0, v7, vcc
	v_mov_b32_e32 v6, v220
	v_mov_b32_e32 v7, v221
	v_lshlrev_b32_e32 v9, 16, v6
	v_and_b32_e32 v6, 0xffff0000, v6
	v_lshlrev_b32_e32 v13, 16, v7
	v_mul_f32_e32 v6, 0xbfb8aa3b, v6
	v_mul_f32_e32 v9, 0xbfb8aa3b, v9
	v_exp_f32_e32 v14, v6
	v_mul_f32_e32 v6, 0xbfb8aa3b, v13
	v_exp_f32_e32 v12, v9
	v_exp_f32_e32 v13, v6
	v_and_b32_e32 v7, 0xffff0000, v7
	v_mul_f32_e32 v6, 0xbfb8aa3b, v7
	v_exp_f32_e32 v15, v6
	v_lshlrev_b64 v[6:7], 12, v[10:11]
	v_lshl_add_u64 v[16:17], v[0:1], 0, v[6:7]
	v_lshlrev_b64 v[6:7], 11, v[10:11]
	v_pk_add_f32 v[10:11], v[12:13], 1.0 op_sel_hi:[1,0]
	v_lshl_add_u64 v[18:19], v[2:3], 0, v[6:7]
	v_div_scale_f32 v12, s[26:27], v11, v11, 1.0
	v_rcp_f32_e32 v13, v12
	ds_read_b128 v[6:9], v8
	v_fma_f32 v20, -v12, v13, 1.0
	v_fmac_f32_e32 v13, v20, v13
	v_div_scale_f32 v20, vcc, 1.0, v11, 1.0
	v_mul_f32_e32 v21, v20, v13
	v_fma_f32 v22, -v12, v21, v20
	v_fmac_f32_e32 v21, v22, v13
	v_fma_f32 v12, -v12, v21, v20
	v_div_fmas_f32 v12, v12, v13, v21
	v_div_fixup_f32 v21, v12, v11, 1.0
	v_div_scale_f32 v11, s[26:27], v10, v10, 1.0
	v_rcp_f32_e32 v12, v11
	s_waitcnt lgkmcnt(0)
; DEVI float sigmoidf_(float x) { return 1.f / (1.f + __expf(-x)); }
; DEVI char* wsp(const Params& P, size_t off) { asm volatile("" : "+s"(off)); return P.ws + off; }
; DEVI int ltid() { int t = threadIdx.x; asm volatile("" : "+v"(t)); return t; }
; DEVI void phase_xcopy(const Params& P) {
;   const int tid = ltid();
;   bfu* xb = (bfu*)wsp(P, O_XB);
;   for (int it = blockIdx.x; it < 16640; it += gridDim.x) {
;     TokInfo ti = tokinfo(it);
;     const float* src = ti.sample ? P.in[1] + (long)(ti.seq * 32 + ti.t) * 1024 : P.in[0] + (long)(ti.seq * 4096 + ti.t) * 1024;
;     float* dst = xrow(P, it);
;     int c = tid * 4;
;     float4 v = *reinterpret_cast<const float4*>(src + c);
;     *reinterpret_cast<float4*>(dst + c) = v;
;     uint2 r;
;     r.x = f2b(v.x) | ((unsigned)f2b(v.y) << 16);
;     r.y = f2b(v.z) | ((unsigned)f2b(v.w) << 16);
;     *reinterpret_cast<uint2*>(xb + (long)it * 1024 + c) = r;
;   }
; }
; template <int BR, int IN, int OUT>
; DEVI void p6_branch(const Params& P, int pm, int pn, float* macc, char* smem, int tid) {
;     ...
; #pragma unroll 8
;   for (int q = 0; q < 16; ++q) {
;     const int id = tid + 256 * q, row = id >> 5, c4 = id & 31;
;     const long grow = (long)pm * 128 + row;
;     const int gcol = pn * 128 + c4 * 4;
;     float4 a = *reinterpret_cast<const float4*>(T + row * 128 + c4 * 4);
;     float g[4];
;     load4bf(Z + grow * NCOL + (9 + BR) * 1024 + gcol, g);
;     float v[4] = {sigmoidf_(g[0]) * a.x, sigmoidf_(g[1]) * a.y, sigmoidf_(g[2]) * a.z, sigmoidf_(g[3]) * a.w};
;     if (IN == 1) {
;       float mo[4]; load4bf(M + grow * 1024 + gcol, mo);
;       v[0] += mo[0]; v[1] += mo[1]; v[2] += mo[2]; v[3] += mo[3];
;     }
;     if (IN == 2) {
;       float4 mo = *reinterpret_cast<const float4*>(macc + grow * 1024 + gcol);
;       v[0] += mo.x; v[1] += mo.y; v[2] += mo.z; v[3] += mo.w;
;     }
;     if (OUT == 1) *reinterpret_cast<float4*>(macc + grow * 1024 + gcol) = make_float4(v[0], v[1], v[2], v[3]);
;     else store4bf(M + grow * 1024 + gcol, v);
;   }
	v_mov_b32_e32 v23, v8
	v_fma_f32 v13, -v11, v12, 1.0
	v_fmac_f32_e32 v12, v13, v12
	v_div_scale_f32 v13, vcc, 1.0, v10, 1.0
	v_mul_f32_e32 v20, v13, v12
	v_fma_f32 v22, -v11, v20, v13
	v_fmac_f32_e32 v20, v22, v12
	v_fma_f32 v11, -v11, v20, v13
	v_div_fmas_f32 v11, v11, v12, v20
	v_div_fixup_f32 v20, v11, v10, 1.0
	v_pk_add_f32 v[10:11], v[14:15], 1.0 op_sel_hi:[1,0]
	v_mov_b32_e32 v22, v6
	v_div_scale_f32 v6, s[26:27], v11, v11, 1.0
	v_rcp_f32_e32 v8, v6
	s_nop 0
	v_fma_f32 v12, -v6, v8, 1.0
	v_fmac_f32_e32 v8, v12, v8
	v_div_scale_f32 v12, vcc, 1.0, v11, 1.0
	v_mul_f32_e32 v13, v12, v8
	v_fma_f32 v14, -v6, v13, v12
	v_fmac_f32_e32 v13, v14, v8
	v_fma_f32 v6, -v6, v13, v12
	v_div_fmas_f32 v6, v6, v8, v13
	v_div_fixup_f32 v15, v6, v11, 1.0
	v_div_scale_f32 v6, s[26:27], v10, v10, 1.0
	v_rcp_f32_e32 v8, v6
	s_nop 0
	v_fma_f32 v11, -v6, v8, 1.0
	v_fmac_f32_e32 v8, v11, v8
	v_div_scale_f32 v11, vcc, 1.0, v10, 1.0
	v_mul_f32_e32 v12, v11, v8
	v_fma_f32 v13, -v6, v12, v11
	v_fmac_f32_e32 v12, v13, v8
	v_fma_f32 v6, -v6, v12, v11
	v_div_fmas_f32 v6, v6, v8, v12
	v_div_fixup_f32 v14, v6, v10, 1.0
	v_mov_b32_e32 v10, v224
	v_mov_b32_e32 v11, v225
	v_mov_b32_e32 v12, v226
	v_mov_b32_e32 v13, v227
	v_mov_b32_e32 v8, v7
	v_mov_b32_e32 v6, v10
	v_mov_b32_e32 v7, v12
	v_pk_fma_f32 v[6:7], v[22:23], v[20:21], v[6:7]
	v_mov_b32_e32 v12, v11
	v_pk_fma_f32 v[8:9], v[8:9], v[14:15], v[12:13]
	v_and_b32_sdwa v10, v7, v95 dst_sel:DWORD dst_unused:UNUSED_PAD src0_sel:WORD_1 src1_sel:DWORD
	v_and_b32_sdwa v11, v6, v95 dst_sel:DWORD dst_unused:UNUSED_PAD src0_sel:WORD_1 src1_sel:DWORD
	v_add3_u32 v6, v6, v11, s39
	v_add3_u32 v7, v7, v10, s39
	v_and_b32_sdwa v10, v9, v95 dst_sel:DWORD dst_unused:UNUSED_PAD src0_sel:WORD_1 src1_sel:DWORD
	v_and_b32_sdwa v11, v8, v95 dst_sel:DWORD dst_unused:UNUSED_PAD src0_sel:WORD_1 src1_sel:DWORD
	v_add3_u32 v9, v9, v10, s39
	v_add3_u32 v8, v8, v11, s39
	v_and_b32_e32 v9, 0xffff0000, v9
	v_and_b32_e32 v8, 0xffff0000, v8
	v_or_b32_sdwa v7, v9, v7 dst_sel:DWORD dst_unused:UNUSED_PAD src0_sel:DWORD src1_sel:WORD_1
	v_or_b32_sdwa v6, v8, v6 dst_sel:DWORD dst_unused:UNUSED_PAD src0_sel:DWORD src1_sel:WORD_1
	global_store_dwordx2 v[18:19], v[6:7], off
	s_cbranch_scc1 .LBB0_741
	s_add_i32 s2, s2, s23
	s_cmp_lt_i32 s2, s1
	s_cbranch_scc1 .LBB0_730
.LBB0_743:
	v_readlane_b32 s60, v252, 36
	s_cmp_lg_u32 s60, 0
	s_cbranch_scc1 .Ltb_skip_b
	v_readlane_b32 s60, v252, 32
	s_cmpk_lt_u32 s60, 0x100
	s_cbranch_scc1 .Ltb_skip_b
	s_cmp_lg_u32 s0, 0
	s_cbranch_scc1 .Ltb_skip_b
	v_readlane_b32 s44, v253, 2
	v_readlane_b32 s45, v253, 3
	v_readlane_b32 s60, v252, 32
	s_nop 4
	s_load_dwordx2 s[42:43], s[44:45], 0x0
	v_lshlrev_b32_e32 v248, 4, v93
	v_lshlrev_b32_e32 v250, 3, v93
	v_mov_b32_e32 v251, 0
	v_lshl_add_u64 v[250:251], v[64:65], 0, v[250:251]
	s_waitcnt lgkmcnt(0)

; DEVI char* wsp(const Params& P, size_t off) { asm volatile("" : "+s"(off)); return P.ws + off; }
; DEVI int ltid() { int t = threadIdx.x; asm volatile("" : "+v"(t)); return t; }
; #define ZERO_ACC(a) _Pragma("unroll") for (int m_ = 0; m_ < 4; ++m_) _Pragma("unroll") for (int n_ = 0; n_ < 4; ++n_) a[m_][n_] = f32x4{0.f, 0.f, 0.f, 0.f}
; DEVI void stage_tile(const bfu* __restrict__ g, int ld, int k0, char* lds, int tid) {
; #pragma unroll
;   for (int i = 0; i < 4; ++i) {
;     int b = tid * 16 + i * 4096;
;     int r = b >> 7, cp = (b >> 4) & 7, gc = cp ^ (r & 7);
;     __builtin_amdgcn_global_load_lds((const unsigned*)(g + (long)r * ld + k0 + gc * 8),
;                                      (unsigned*)(lds + b), 16, 0, 0);
;   }
; }
; DEVI void phase9(const Params& P, int l, int pass, char* smem) {
;   const int tid = ltid();
;   const int ntok = pass ? 8192 : 8448, base = pass ? 8448 : 0;
;   const int nM = ntok / 128, nN = 16;
;   const bfu* xb = (const bfu*)wsp(P, O_XB) + (long)base * 1024;
;   const bfu* W = (const bfu*)wsp(P, O_WQ);
;   bfu* qp = (bfu*)wsp(P, O_QP);
;   const bfu* KB = (const bfu*)wsp(P, O_KEYS);
;   float* sc = (float*)wsp(P, O_AU);
;   for (int id = blockIdx.x; id < nM * nN; id += gridDim.x) {
;     int pm, pn; tile_rc_m(id, nM, nN, pm, pn);
;     {
;       f32x4 acc[4][4]; ZERO_ACC(acc);
;       gemm_core(acc, xb + (long)pm * 128 * 1024, 1024, W + (long)pn * 128 * 1024, 1024, 1024, smem, tid);
;       epi_store_bf16(acc, nullptr, qp + (long)pm * 128 * 2048 + pn * 128, 2048, smem, tid);
.Ltb_skip_g:
	s_cmp_eq_u32 s90, 0
	s_cselect_b64 s[48:49], -1, 0
	s_and_b64 s[26:27], s[48:49], exec
	s_movk_i32 s1, 0x420
	s_cselect_b32 s1, s1, 0x400
	v_mov_b32_e32 v91, v93
	s_mov_b64 s[40:41], 0x6502000
	s_mov_b64 s[26:27], 0x2000000
	s_mov_b64 s[42:43], 0xa682000
	s_mov_b64 s[44:45], 0x2400000
	s_mov_b64 s[46:47], 0x18d82000
	s_cmp_ge_i32 s74, s1
	s_cbranch_scc1 .LBB0_951
	v_lshlrev_b32_e32 v196, 4, v91
	v_add_u32_e32 v199, 0x3000, v196
	v_lshrrev_b32_e32 v5, 4, v91
	v_ashrrev_i32_e32 v18, 7, v199
	v_and_b32_e32 v24, 7, v91
	v_xor_b32_e32 v17, v18, v91
	v_bitop3_b32 v5, v5, v24, 3 bitop3:0x6c
	v_bfe_u32 v11, v91, 4, 2
	v_lshlrev_b32_e32 v17, 3, v17
	v_lshlrev_b32_e32 v200, 4, v5
	v_lshlrev_b32_e32 v5, 7, v91
	v_and_b32_e32 v22, 56, v17
	v_and_b32_e32 v17, 15, v91
	v_lshrrev_b32_e32 v23, 1, v91
	s_mov_b32 s4, 0x1ffffc0
	v_and_b32_e32 v202, 0x2780, v5
	v_bitop3_b32 v5, v11, v24, 4 bitop3:0x36
	v_lshrrev_b32_e32 v11, 2, v91
	v_and_or_b32 v17, v23, s4, v17
	v_and_b32_e32 v11, 12, v11
	s_mov_b32 s4, 0xfffffc0
	v_ashrrev_i32_e32 v26, 4, v91
	v_lshlrev_b32_e32 v201, 7, v17
	v_and_or_b32 v17, v23, s4, v11
	s_movk_i32 s4, 0x110
	v_ashrrev_i32_e32 v27, 31, v26
	v_mul_lo_u32 v25, v26, s4
	v_lshlrev_b64 v[100:101], 12, v[26:27]
	v_add_u32_e32 v26, 0x100, v91
	v_ashrrev_i32_e32 v26, 4, v26
	v_ashrrev_i32_e32 v27, 31, v26
	v_mul_lo_u32 v28, v26, s4
	v_lshlrev_b64 v[102:103], 12, v[26:27]
	v_add_u32_e32 v26, 0x200, v91
	v_ashrrev_i32_e32 v26, 4, v26
	v_ashrrev_i32_e32 v27, 31, v26
	v_mul_lo_u32 v29, v26, s4
	v_lshlrev_b64 v[104:105], 12, v[26:27]
	v_add_u32_e32 v26, 0x300, v91
	v_ashrrev_i32_e32 v26, 4, v26
	s_add_u32 s2, s30, s40
	v_ashrrev_i32_e32 v27, 31, v26
	s_addc_u32 s24, s31, s41
	v_mul_lo_u32 v30, v26, s4
	v_lshlrev_b64 v[106:107], 12, v[26:27]
	v_add_u32_e32 v26, 0x400, v91
	s_and_b64 s[48:49], s[48:49], exec
	v_ashrrev_i32_e32 v26, 4, v26
	s_cselect_b32 s52, 0, 0x1080000
	v_ashrrev_i32_e32 v27, 31, v26
	s_add_u32 s2, s2, s52
	v_mul_lo_u32 v31, v26, s4
	v_lshlrev_b64 v[108:109], 12, v[26:27]
	v_add_u32_e32 v26, 0x500, v91
	s_addc_u32 s24, s24, 0
	v_ashrrev_i32_e32 v26, 4, v26
	s_add_u32 s48, s30, s26
	v_ashrrev_i32_e32 v27, 31, v26
	s_addc_u32 s49, s31, s27
	v_mul_lo_u32 v32, v26, s4
	v_lshlrev_b64 v[110:111], 12, v[26:27]
	v_add_u32_e32 v26, 0x600, v91
	s_add_u32 s50, s30, s42
	v_ashrrev_i32_e32 v26, 4, v26
	s_addc_u32 s51, s31, s43
	v_ashrrev_i32_e32 v27, 31, v26
	s_add_u32 s44, s30, s44
	v_mul_lo_u32 v33, v26, s4
	v_lshlrev_b64 v[112:113], 12, v[26:27]
	v_add_u32_e32 v26, 0x700, v91
	s_addc_u32 s45, s31, s45
	v_ashrrev_i32_e32 v0, 3, v91
	v_ashrrev_i32_e32 v26, 4, v26
	s_add_u32 s42, s30, s46
	v_ashrrev_i32_e32 v1, 31, v0
	v_add_u32_e32 v197, 0x1000, v196
	v_mul_lo_u32 v17, v17, s4
	v_mul_lo_u32 v34, v26, s4
	s_mov_b32 s4, 0x7fffc0
	s_addc_u32 s43, s31, s47
	v_xor_b32_e32 v4, v0, v91
	v_lshlrev_b64 v[2:3], 10, v[0:1]
	v_ashrrev_i32_e32 v6, 7, v197
	v_ashrrev_i32_e32 v27, 31, v26
	v_lshlrev_b64 v[116:117], 11, v[0:1]
	v_lshlrev_b64 v[124:125], 7, v[0:1]
	v_and_or_b32 v1, v23, s4, v11
	v_and_b32_e32 v132, 0x1f0, v196
	v_mov_b32_e32 v133, v89
	v_bitop3_b32 v0, v0, 7, v91 bitop3:0x48
	v_readlane_b32 s4, v252, 25
	v_ashrrev_i32_e32 v7, 31, v6
	v_add_u32_e32 v198, 0x2000, v196
	v_lshlrev_b32_e32 v203, 4, v5
	v_and_b32_e32 v5, 0x4f, v91
	v_lshlrev_b64 v[114:115], 12, v[26:27]
	v_lshlrev_b32_e32 v1, 9, v1
	v_lshl_add_u64 v[134:135], s[42:43], 0, v[132:133]
	v_lshl_add_u64 v[26:27], s[40:41], 0, v[116:117]
	v_lshlrev_b32_e32 v88, 4, v0
	v_readlane_b32 s5, v252, 26
	s_add_u32 s42, s4, s52
	v_ashrrev_i32_e32 v12, 7, v198
	v_lshl_add_u32 v204, v5, 1, v17
	v_lshlrev_b64 v[118:119], 11, v[6:7]
	v_lshl_or_b32 v205, v5, 2, v1
	v_lshl_add_u64 v[0:1], v[26:27], 0, v[88:89]
	s_addc_u32 s43, s5, 0
	v_bitop3_b32 v5, v6, 7, v91 bitop3:0x48
	v_xor_b32_e32 v10, v6, v91
	v_lshlrev_b64 v[8:9], 10, v[6:7]
	v_ashrrev_i32_e32 v13, 31, v12
	v_lshlrev_b64 v[126:127], 7, v[6:7]
	v_lshl_add_u64 v[136:137], s[42:43], 0, v[0:1]
	v_lshl_add_u64 v[0:1], s[40:41], 0, v[118:119]
	v_lshlrev_b32_e32 v6, 4, v5
	v_mov_b32_e32 v7, v89
	v_lshlrev_b64 v[120:121], 11, v[12:13]
	v_lshl_add_u64 v[0:1], v[0:1], 0, v[6:7]
	v_bitop3_b32 v5, v12, 7, v91 bitop3:0x48
	v_xor_b32_e32 v16, v12, v91
	v_lshlrev_b64 v[14:15], 10, v[12:13]
	v_ashrrev_i32_e32 v19, 31, v18
	v_lshlrev_b64 v[128:129], 7, v[12:13]
	v_lshl_add_u64 v[138:139], s[42:43], 0, v[0:1]
	v_lshl_add_u64 v[0:1], s[40:41], 0, v[120:121]
	v_lshlrev_b32_e32 v12, 4, v5
	v_mov_b32_e32 v13, v89
	v_lshlrev_b64 v[122:123], 11, v[18:19]
	v_lshl_add_u64 v[0:1], v[0:1], 0, v[12:13]
	v_bitop3_b32 v5, v18, 7, v91 bitop3:0x48
	v_lshlrev_b64 v[20:21], 10, v[18:19]
	v_lshlrev_b64 v[130:131], 7, v[18:19]
	v_lshl_add_u64 v[140:141], s[42:43], 0, v[0:1]
	v_lshl_add_u64 v[0:1], s[40:41], 0, v[122:123]
	v_lshlrev_b32_e32 v18, 4, v5
	v_mov_b32_e32 v19, v89
	v_lshl_add_u64 v[0:1], v[0:1], 0, v[18:19]
	v_lshl_add_u64 v[142:143], s[42:43], 0, v[0:1]
	v_lshl_add_u64 v[0:1], s[26:27], 0, v[116:117]
	v_lshl_add_u64 v[0:1], v[0:1], 0, v[88:89]
	v_lshl_add_u64 v[144:145], s[4:5], 0, v[0:1]
	v_lshl_add_u64 v[0:1], s[26:27], 0, v[118:119]
	v_lshl_add_u64 v[0:1], v[0:1], 0, v[6:7]
	v_lshl_add_u64 v[146:147], s[4:5], 0, v[0:1]
	v_lshl_add_u64 v[0:1], s[26:27], 0, v[120:121]
	v_lshlrev_b32_e32 v17, 3, v91
	v_lshl_add_u64 v[0:1], v[0:1], 0, v[12:13]
	v_lshlrev_b32_e32 v4, 3, v4
	v_lshlrev_b32_e32 v10, 3, v10
	v_lshlrev_b32_e32 v16, 3, v16
	v_and_b32_e32 v24, 0x78, v17
	v_lshl_add_u64 v[148:149], s[4:5], 0, v[0:1]
	v_lshl_add_u64 v[0:1], s[26:27], 0, v[122:123]
	v_and_b32_e32 v4, 56, v4
	v_and_b32_e32 v10, 56, v10
	v_and_b32_e32 v16, 56, v16
	v_lshlrev_b32_e32 v17, 1, v24
	v_lshl_add_u64 v[0:1], v[0:1], 0, v[18:19]
	s_movk_i32 s37, 0x110
	v_lshl_add_u64 v[150:151], s[4:5], 0, v[0:1]
	v_lshlrev_b64 v[152:153], 1, v[2:3]
	v_lshlrev_b32_e32 v88, 1, v4
	v_lshlrev_b64 v[154:155], 1, v[8:9]
	v_lshlrev_b32_e32 v156, 1, v10
	v_lshlrev_b64 v[158:159], 1, v[14:15]
	v_lshlrev_b32_e32 v160, 1, v16
	v_lshlrev_b64 v[162:163], 1, v[20:21]
	v_lshlrev_b32_e32 v164, 1, v22
	v_lshlrev_b32_e32 v166, 1, v24
	v_add_u32_e32 v133, v17, v25
	v_add_u32_e32 v206, v17, v28
	v_add_u32_e32 v207, v17, v29
	v_add_u32_e32 v208, v17, v30
	v_add_u32_e32 v209, v17, v31
	v_add_u32_e32 v210, v17, v32
	v_add_u32_e32 v211, v17, v33
	v_add_u32_e32 v212, v17, v34
	s_mov_b32 s46, s74

; DEVI void convert_chunk_fp8(const float* __restrict__ src, unsigned char* __restrict__ dst, float scale, int tid) {
;   int o = tid * 16;
;   uint4 r;
;   unsigned rr[4];
; #pragma unroll
;   for (int q = 0; q < 4; ++q) {
;     float4 a = *reinterpret_cast<const float4*>(src + o + q * 4);
;     int p = __builtin_amdgcn_cvt_pk_fp8_f32(a.x * scale, a.y * scale, 0, false);
;     p = __builtin_amdgcn_cvt_pk_fp8_f32(a.z * scale, a.w * scale, p, true);
;     rr[q] = (unsigned)p;
;   }
;   r = make_uint4(rr[0], rr[1], rr[2], rr[3]);
;   *reinterpret_cast<uint4*>(dst + o) = r;
; }
; DEVI void phase9(const Params& P, int l, int pass, char* smem) {
;     ...
;       const float* T = reinterpret_cast<const float*>(smem);
; #pragma unroll 8
;       for (int q = 0; q < 16; ++q) {
;         const int id2 = tid + 256 * q, row = id2 >> 5, c4 = id2 & 31;
;         *reinterpret_cast<float4*>(sc + (long)(pm * 128 + row) * 2048 + pn * 128 + c4 * 4) =
;             *reinterpret_cast<const float4*>(T + row * 128 + c4 * 4);
;       }
.LBB0_949:
	v_add_u32_e32 v8, s27, v91
	v_ashrrev_i32_e32 v2, 5, v8
	v_lshl_or_b32 v4, v2, 9, v132
	v_add_u32_e32 v2, s26, v2
	v_ashrrev_i32_e32 v3, 31, v2
	v_lshlrev_b64 v[2:3], 13, v[2:3]
	v_lshl_add_u64 v[6:7], v[0:1], 0, v[2:3]
	ds_read_b128 v[2:5], v4
	s_addk_i32 s27, 0x800
	s_cmpk_eq_i32 s27, 0x1000
	s_waitcnt lgkmcnt(0)
	global_store_dwordx4 v[6:7], v[2:5], off
	s_nop 1
	v_add_u32_e32 v2, 0x100, v8
	v_ashrrev_i32_e32 v2, 5, v2
	v_lshl_or_b32 v4, v2, 9, v132
	v_add_u32_e32 v2, s26, v2
	v_ashrrev_i32_e32 v3, 31, v2
	v_lshlrev_b64 v[2:3], 13, v[2:3]
	v_lshl_add_u64 v[6:7], v[0:1], 0, v[2:3]
	ds_read_b128 v[2:5], v4
	s_waitcnt lgkmcnt(0)
	global_store_dwordx4 v[6:7], v[2:5], off
	s_nop 1
	v_add_u32_e32 v2, 0x200, v8
	v_ashrrev_i32_e32 v2, 5, v2
	v_lshl_or_b32 v4, v2, 9, v132
	v_add_u32_e32 v2, s26, v2
	v_ashrrev_i32_e32 v3, 31, v2
	v_lshlrev_b64 v[2:3], 13, v[2:3]
	v_lshl_add_u64 v[6:7], v[0:1], 0, v[2:3]
	ds_read_b128 v[2:5], v4
	s_waitcnt lgkmcnt(0)
	global_store_dwordx4 v[6:7], v[2:5], off
	s_nop 1
	v_add_u32_e32 v2, 0x300, v8
	v_ashrrev_i32_e32 v2, 5, v2
	v_lshl_or_b32 v4, v2, 9, v132
	v_add_u32_e32 v2, s26, v2
	v_ashrrev_i32_e32 v3, 31, v2
	v_lshlrev_b64 v[2:3], 13, v[2:3]
	v_lshl_add_u64 v[6:7], v[0:1], 0, v[2:3]
	ds_read_b128 v[2:5], v4
	s_waitcnt lgkmcnt(0)
	global_store_dwordx4 v[6:7], v[2:5], off
	s_nop 1
	v_add_u32_e32 v2, 0x400, v8
	v_ashrrev_i32_e32 v2, 5, v2
	v_lshl_or_b32 v4, v2, 9, v132
	v_add_u32_e32 v2, s26, v2
	v_ashrrev_i32_e32 v3, 31, v2
	v_lshlrev_b64 v[2:3], 13, v[2:3]
	v_lshl_add_u64 v[6:7], v[0:1], 0, v[2:3]
	ds_read_b128 v[2:5], v4
	s_waitcnt lgkmcnt(0)
	global_store_dwordx4 v[6:7], v[2:5], off
	s_nop 1
	v_add_u32_e32 v2, 0x500, v8
	v_ashrrev_i32_e32 v2, 5, v2
	v_lshl_or_b32 v4, v2, 9, v132
	v_add_u32_e32 v2, s26, v2
	v_ashrrev_i32_e32 v3, 31, v2
	v_lshlrev_b64 v[2:3], 13, v[2:3]
	v_lshl_add_u64 v[6:7], v[0:1], 0, v[2:3]
	ds_read_b128 v[2:5], v4
	s_waitcnt lgkmcnt(0)
	global_store_dwordx4 v[6:7], v[2:5], off
	s_nop 1
	v_add_u32_e32 v2, 0x600, v8
	v_ashrrev_i32_e32 v2, 5, v2
	v_lshl_or_b32 v4, v2, 9, v132
	v_add_u32_e32 v2, s26, v2
	v_ashrrev_i32_e32 v3, 31, v2
	v_lshlrev_b64 v[2:3], 13, v[2:3]
	v_lshl_add_u64 v[6:7], v[0:1], 0, v[2:3]
	ds_read_b128 v[2:5], v4
	s_waitcnt lgkmcnt(0)
	global_store_dwordx4 v[6:7], v[2:5], off
	s_nop 1
	v_add_u32_e32 v2, 0x700, v8
	v_ashrrev_i32_e32 v2, 5, v2
	v_lshl_or_b32 v4, v2, 9, v132
	v_add_u32_e32 v2, s26, v2
	v_ashrrev_i32_e32 v3, 31, v2
	v_lshlrev_b64 v[2:3], 13, v[2:3]
	v_lshl_add_u64 v[6:7], v[0:1], 0, v[2:3]
	ds_read_b128 v[2:5], v4
	s_waitcnt lgkmcnt(0)
	global_store_dwordx4 v[6:7], v[2:5], off
	s_cbranch_scc0 .LBB0_949
	s_add_i32 s46, s46, s23
	s_cmp_ge_i32 s46, s1
	s_cbranch_scc0 .LBB0_942
.LBB0_951:
	v_readlane_b32 s60, v252, 36
	s_cmp_lg_u32 s60, 0
	s_cbranch_scc1 .Ltb_skip_h
	v_readlane_b32 s60, v252, 32
	s_cmpk_lt_u32 s60, 0x100
	s_cbranch_scc1 .Ltb_skip_h
	v_readlane_b32 s54, v253, 22
	v_readlane_b32 s55, v253, 23
	v_readlane_b32 s56, v253, 24
	v_readlane_b32 s57, v253, 25
	s_lshl_b32 s61, s0, 26
	s_add_u32 s54, s54, s61
	s_addc_u32 s55, s55, 0
	s_add_u32 s56, s56, s61
	s_addc_u32 s57, s57, 0
	v_lshlrev_b32_e32 v248, 6, v93
	v_lshlrev_b32_e32 v250, 4, v93
	v_mov_b32_e32 v251, 0
	v_lshl_add_u64 v[250:251], v[64:65], 0, v[250:251]
